# G3 mid-K rescale: second batch of 16 gate loads software-pipelined (7 destination quads renamed into free VGPRs and issued behind batch 1, 9 issued as batch 1 releases their registers), vmcnt recomput
# speedup vs baseline: 1.0037x; 1.0000x over previous
.LBB0_1021:
	s_cmp_eq_u32 s0, 0
	s_cselect_b64 s[2:3], -1, 0
	s_and_b32 s28, s0, 6
	s_cmp_lg_u32 s28, 0
	s_cselect_b64 s[28:29], -1, 0
	s_or_b64 s[2:3], s[2:3], s[28:29]
	s_and_b64 vcc, exec, s[2:3]
	s_cbranch_vccnz .LBB0_1023
	v_readfirstlane_b32 s90, v180
	v_readfirstlane_b32 s91, v181
	s_nop 1
	v_subrev_u32_e32 v251, s90, v180
	s_mov_b32 s2, 0xffff0000
	s_mov_b32 s2, 0xffff4000
	s_mov_b32 s2, 0xffef6000
	s_mov_b32 s2, 0xffff6000
	s_mov_b32 s2, 0xffef8000
	s_movk_i32 s2, 0x8000
	s_mov_b32 s2, 0xffefa000
	s_movk_i32 s2, 0xa000
	s_mov_b32 s2, 0xffefc000
	s_movk_i32 s2, 0xc000
	s_mov_b32 s2, 0xffefe000
	s_movk_i32 s2, 0xe000
	s_mov_b32 s2, 0xfff00000
	s_add_u32 s88, s90, 0xffee2000
	s_addc_u32 s89, s91, -1
	global_load_dwordx4 v[196:199], v251, s[88:89] nt
	s_add_u32 s88, s90, 0xfffe2000
	s_addc_u32 s89, s91, -1
	global_load_dwordx4 v[202:205], v251, s[88:89] nt
	s_add_u32 s88, s90, 0xffee4000
	s_addc_u32 s89, s91, -1
	global_load_dwordx4 v[206:209], v251, s[88:89] nt
	s_add_u32 s88, s90, 0xfffe4000
	s_addc_u32 s89, s91, -1
	global_load_dwordx4 v[210:213], v251, s[88:89] nt
	s_add_u32 s88, s90, 0xffee6000
	s_addc_u32 s89, s91, -1
	global_load_dwordx4 v[176:179], v251, s[88:89] nt
	s_add_u32 s88, s90, 0xfffe6000
	s_addc_u32 s89, s91, -1
	global_load_dwordx4 v[172:175], v251, s[88:89] nt
	s_add_u32 s88, s90, 0xffee8000
	s_addc_u32 s89, s91, -1
	global_load_dwordx4 v[168:171], v251, s[88:89] nt
	s_add_u32 s88, s90, 0xfffe8000
	s_addc_u32 s89, s91, -1
	global_load_dwordx4 v[164:167], v251, s[88:89] nt
	s_add_u32 s88, s90, 0xffeea000
	s_addc_u32 s89, s91, -1
	global_load_dwordx4 v[160:163], v251, s[88:89] nt
	s_add_u32 s88, s90, 0xfffea000
	s_addc_u32 s89, s91, -1
	global_load_dwordx4 v[156:159], v251, s[88:89] nt
	s_add_u32 s88, s90, 0xffeec000
	s_addc_u32 s89, s91, -1
	global_load_dwordx4 v[152:155], v251, s[88:89] nt
	s_add_u32 s88, s90, 0xfffec000
	s_addc_u32 s89, s91, -1
	global_load_dwordx4 v[148:151], v251, s[88:89] nt
	s_add_u32 s88, s90, 0xffeee000
	s_addc_u32 s89, s91, -1
	global_load_dwordx4 v[144:147], v251, s[88:89] nt
	s_add_u32 s88, s90, 0xfffee000
	s_addc_u32 s89, s91, -1
	global_load_dwordx4 v[140:143], v251, s[88:89] nt
	s_add_u32 s88, s90, 0xffef0000
	s_addc_u32 s89, s91, -1
	global_load_dwordx4 v[136:139], v251, s[88:89] nt
	s_nop 0
	s_add_u32 s88, s90, 0xffff0000
	s_addc_u32 s89, s91, -1
	global_load_dwordx4 v[132:135], v251, s[88:89] nt
	s_add_u32 s88, s90, 0xffef2000
	s_addc_u32 s89, s91, -1
	global_load_dwordx4 v[222:225], v251, s[88:89] nt
	s_add_u32 s88, s90, 0xffff8000
	s_addc_u32 s89, s91, -1
	global_load_dwordx4 v[226:229], v251, s[88:89] nt
	s_add_u32 s88, s90, 0xffffa000
	s_addc_u32 s89, s91, -1
	global_load_dwordx4 v[230:233], v251, s[88:89] nt
	s_add_u32 s88, s90, 0xffffc000
	s_addc_u32 s89, s91, -1
	global_load_dwordx4 v[234:237], v251, s[88:89] nt
	s_add_u32 s88, s90, 0xffffe000
	s_addc_u32 s89, s91, -1
	global_load_dwordx4 v[238:241], v251, s[88:89] nt
	s_add_u32 s88, s90, 0xfff00000
	s_addc_u32 s89, s91, -1
	global_load_dwordx4 v[242:245], v251, s[88:89] nt
	global_load_dwordx4 v[246:249], v251, s[90:91] nt
	s_waitcnt vmcnt(22)
	v_lshlrev_b32_e32 v182, 16, v196
	v_and_b32_e32 v183, 0xffff0000, v196
	v_rcp_f32_e32 v182, v182
	v_rcp_f32_e32 v183, v183
	s_waitcnt vmcnt(21)
	v_lshlrev_b32_e32 v188, 16, v202
	v_and_b32_e32 v189, 0xffff0000, v202
	v_pk_mul_f32 v[182:183], v[182:183], v[188:189]
	v_lshlrev_b32_e32 v188, 16, v197
	v_and_b32_e32 v189, 0xffff0000, v197
	v_rcp_f32_e32 v188, v188
	v_rcp_f32_e32 v189, v189
	v_pk_mul_f32 v[128:129], v[128:129], v[182:183]
	v_lshlrev_b32_e32 v182, 16, v203
	v_and_b32_e32 v183, 0xffff0000, v203
	v_pk_mul_f32 v[182:183], v[188:189], v[182:183]
	v_lshlrev_b32_e32 v188, 16, v198
	v_and_b32_e32 v189, 0xffff0000, v198
	v_rcp_f32_e32 v188, v188
	v_rcp_f32_e32 v189, v189
	v_pk_mul_f32 v[130:131], v[130:131], v[182:183]
	v_lshlrev_b32_e32 v182, 16, v204
	v_and_b32_e32 v183, 0xffff0000, v204
	v_pk_mul_f32 v[182:183], v[188:189], v[182:183]
	v_lshlrev_b32_e32 v188, 16, v199
	v_and_b32_e32 v189, 0xffff0000, v199
	s_add_u32 s88, s90, 0xffef4000
	s_addc_u32 s89, s91, -1
	global_load_dwordx4 v[196:199], v251, s[88:89] nt
	v_rcp_f32_e32 v188, v188
	v_rcp_f32_e32 v189, v189
	v_pk_mul_f32 v[124:125], v[124:125], v[182:183]
	v_lshlrev_b32_e32 v182, 16, v205
	v_and_b32_e32 v183, 0xffff0000, v205
	s_add_u32 s88, s90, 0xffff4000
	s_addc_u32 s89, s91, -1
	global_load_dwordx4 v[202:205], v251, s[88:89] nt
	v_pk_mul_f32 v[182:183], v[188:189], v[182:183]
	s_waitcnt vmcnt(22)
	v_lshlrev_b32_e32 v188, 16, v206
	v_and_b32_e32 v189, 0xffff0000, v206
	v_rcp_f32_e32 v188, v188
	v_rcp_f32_e32 v189, v189
	v_pk_mul_f32 v[126:127], v[126:127], v[182:183]
	s_waitcnt vmcnt(21)
	v_lshlrev_b32_e32 v182, 16, v210
	v_and_b32_e32 v183, 0xffff0000, v210
	v_pk_mul_f32 v[182:183], v[188:189], v[182:183]
	v_lshlrev_b32_e32 v188, 16, v207
	v_and_b32_e32 v189, 0xffff0000, v207
	v_rcp_f32_e32 v188, v188
	v_rcp_f32_e32 v189, v189
	v_pk_mul_f32 v[120:121], v[120:121], v[182:183]
	v_lshlrev_b32_e32 v182, 16, v211
	v_and_b32_e32 v183, 0xffff0000, v211
	v_pk_mul_f32 v[182:183], v[188:189], v[182:183]
	v_lshlrev_b32_e32 v188, 16, v208
	v_and_b32_e32 v189, 0xffff0000, v208
	v_rcp_f32_e32 v188, v188
	v_rcp_f32_e32 v189, v189
	v_pk_mul_f32 v[122:123], v[122:123], v[182:183]
	v_lshlrev_b32_e32 v182, 16, v212
	v_and_b32_e32 v183, 0xffff0000, v212
	v_pk_mul_f32 v[182:183], v[188:189], v[182:183]
	v_lshlrev_b32_e32 v188, 16, v209
	v_and_b32_e32 v189, 0xffff0000, v209
	s_add_u32 s88, s90, 0xffef6000
	s_addc_u32 s89, s91, -1
	global_load_dwordx4 v[206:209], v251, s[88:89] nt
	v_rcp_f32_e32 v188, v188
	v_rcp_f32_e32 v189, v189
	v_pk_mul_f32 v[116:117], v[116:117], v[182:183]
	v_lshlrev_b32_e32 v182, 16, v213
	v_and_b32_e32 v183, 0xffff0000, v213
	s_add_u32 s88, s90, 0xffff6000
	s_addc_u32 s89, s91, -1
	global_load_dwordx4 v[210:213], v251, s[88:89] nt
	v_pk_mul_f32 v[182:183], v[188:189], v[182:183]
	s_waitcnt vmcnt(22)
	v_lshlrev_b32_e32 v188, 16, v176
	v_and_b32_e32 v176, 0xffff0000, v176
	v_pk_mul_f32 v[118:119], v[118:119], v[182:183]
	s_waitcnt vmcnt(21)
	v_lshlrev_b32_e32 v182, 16, v172
	v_and_b32_e32 v183, 0xffff0000, v172
	v_lshlrev_b32_e32 v172, 16, v177
	v_rcp_f32_e32 v189, v176
	v_rcp_f32_e32 v176, v172
	v_and_b32_e32 v172, 0xffff0000, v177
	v_rcp_f32_e32 v177, v172
	v_lshlrev_b32_e32 v172, 16, v173
	v_and_b32_e32 v173, 0xffff0000, v173
	v_rcp_f32_e32 v188, v188
	v_pk_mul_f32 v[172:173], v[176:177], v[172:173]
	v_lshlrev_b32_e32 v176, 16, v178
	v_and_b32_e32 v177, 0xffff0000, v178
	v_rcp_f32_e32 v176, v176
	v_rcp_f32_e32 v177, v177
	v_pk_mul_f32 v[114:115], v[114:115], v[172:173]
	v_lshlrev_b32_e32 v172, 16, v174
	v_and_b32_e32 v173, 0xffff0000, v174
	v_lshlrev_b32_e32 v174, 16, v179
	v_pk_mul_f32 v[172:173], v[176:177], v[172:173]
	v_rcp_f32_e32 v176, v174
	v_and_b32_e32 v174, 0xffff0000, v179
	v_rcp_f32_e32 v177, v174
	v_pk_mul_f32 v[108:109], v[108:109], v[172:173]
	v_lshlrev_b32_e32 v172, 16, v175
	v_and_b32_e32 v173, 0xffff0000, v175
	v_pk_mul_f32 v[172:173], v[176:177], v[172:173]
	s_add_u32 s88, s90, 0xffff2000
	s_addc_u32 s89, s91, -1
	global_load_dwordx4 v[176:179], v251, s[88:89] nt
	s_waitcnt vmcnt(21)
	v_lshlrev_b32_e32 v174, 16, v168
	v_and_b32_e32 v168, 0xffff0000, v168
	v_pk_mul_f32 v[110:111], v[110:111], v[172:173]
	s_waitcnt vmcnt(20)
	v_lshlrev_b32_e32 v172, 16, v164
	v_and_b32_e32 v173, 0xffff0000, v164
	v_lshlrev_b32_e32 v164, 16, v169
	v_rcp_f32_e32 v175, v168
	v_rcp_f32_e32 v168, v164
	v_and_b32_e32 v164, 0xffff0000, v169
	v_rcp_f32_e32 v169, v164
	v_lshlrev_b32_e32 v164, 16, v165
	v_and_b32_e32 v165, 0xffff0000, v165
	v_rcp_f32_e32 v174, v174
	v_pk_mul_f32 v[164:165], v[168:169], v[164:165]
	v_lshlrev_b32_e32 v168, 16, v170
	v_and_b32_e32 v169, 0xffff0000, v170
	v_rcp_f32_e32 v168, v168
	v_rcp_f32_e32 v169, v169
	v_pk_mul_f32 v[106:107], v[106:107], v[164:165]
	v_lshlrev_b32_e32 v164, 16, v166
	v_and_b32_e32 v165, 0xffff0000, v166
	v_lshlrev_b32_e32 v166, 16, v171
	v_pk_mul_f32 v[164:165], v[168:169], v[164:165]
	v_rcp_f32_e32 v168, v166
	v_and_b32_e32 v166, 0xffff0000, v171
	v_rcp_f32_e32 v169, v166
	v_pk_mul_f32 v[100:101], v[100:101], v[164:165]
	v_lshlrev_b32_e32 v164, 16, v167
	v_and_b32_e32 v165, 0xffff0000, v167
	v_pk_mul_f32 v[164:165], v[168:169], v[164:165]
	s_add_u32 s88, s90, 0xffef8000
	s_addc_u32 s89, s91, -1
	global_load_dwordx4 v[168:171], v251, s[88:89] nt
	s_waitcnt vmcnt(20)
	v_lshlrev_b32_e32 v166, 16, v160
	v_and_b32_e32 v160, 0xffff0000, v160
	v_pk_mul_f32 v[102:103], v[102:103], v[164:165]
	s_waitcnt vmcnt(19)
	v_lshlrev_b32_e32 v164, 16, v156
	v_and_b32_e32 v165, 0xffff0000, v156
	v_lshlrev_b32_e32 v156, 16, v161
	v_rcp_f32_e32 v167, v160
	v_rcp_f32_e32 v160, v156
	v_and_b32_e32 v156, 0xffff0000, v161
	v_rcp_f32_e32 v161, v156
	v_lshlrev_b32_e32 v156, 16, v157
	v_and_b32_e32 v157, 0xffff0000, v157
	v_rcp_f32_e32 v166, v166
	v_pk_mul_f32 v[156:157], v[160:161], v[156:157]
	v_lshlrev_b32_e32 v160, 16, v162
	v_and_b32_e32 v161, 0xffff0000, v162
	v_rcp_f32_e32 v160, v160
	v_rcp_f32_e32 v161, v161
	v_pk_mul_f32 v[98:99], v[98:99], v[156:157]
	v_lshlrev_b32_e32 v156, 16, v158
	v_and_b32_e32 v157, 0xffff0000, v158
	v_lshlrev_b32_e32 v158, 16, v163
	v_pk_mul_f32 v[156:157], v[160:161], v[156:157]
	v_rcp_f32_e32 v160, v158
	v_and_b32_e32 v158, 0xffff0000, v163
	v_rcp_f32_e32 v161, v158
	v_pk_mul_f32 v[92:93], v[92:93], v[156:157]
	v_lshlrev_b32_e32 v156, 16, v159
	v_and_b32_e32 v157, 0xffff0000, v159
	v_pk_mul_f32 v[156:157], v[160:161], v[156:157]
	s_add_u32 s88, s90, 0xffefa000
	s_addc_u32 s89, s91, -1
	global_load_dwordx4 v[160:163], v251, s[88:89] nt
	s_waitcnt vmcnt(19)
	v_lshlrev_b32_e32 v158, 16, v152
	v_and_b32_e32 v152, 0xffff0000, v152
	v_pk_mul_f32 v[94:95], v[94:95], v[156:157]
	s_waitcnt vmcnt(18)
	v_lshlrev_b32_e32 v156, 16, v148
	v_and_b32_e32 v157, 0xffff0000, v148
	v_lshlrev_b32_e32 v148, 16, v153
	v_rcp_f32_e32 v159, v152
	v_rcp_f32_e32 v152, v148
	v_and_b32_e32 v148, 0xffff0000, v153
	v_rcp_f32_e32 v153, v148
	v_lshlrev_b32_e32 v148, 16, v149
	v_and_b32_e32 v149, 0xffff0000, v149
	v_rcp_f32_e32 v158, v158
	v_pk_mul_f32 v[148:149], v[152:153], v[148:149]
	v_lshlrev_b32_e32 v152, 16, v154
	v_and_b32_e32 v153, 0xffff0000, v154
	v_rcp_f32_e32 v152, v152
	v_rcp_f32_e32 v153, v153
	v_pk_mul_f32 v[90:91], v[90:91], v[148:149]
	v_lshlrev_b32_e32 v148, 16, v150
	v_and_b32_e32 v149, 0xffff0000, v150
	v_lshlrev_b32_e32 v150, 16, v155
	v_pk_mul_f32 v[148:149], v[152:153], v[148:149]
	v_rcp_f32_e32 v152, v150
	v_and_b32_e32 v150, 0xffff0000, v155
	v_rcp_f32_e32 v153, v150
	v_pk_mul_f32 v[84:85], v[84:85], v[148:149]
	v_lshlrev_b32_e32 v148, 16, v151
	v_and_b32_e32 v149, 0xffff0000, v151
	v_pk_mul_f32 v[148:149], v[152:153], v[148:149]
	s_add_u32 s88, s90, 0xffefc000
	s_addc_u32 s89, s91, -1
	global_load_dwordx4 v[152:155], v251, s[88:89] nt
	s_waitcnt vmcnt(18)
	v_lshlrev_b32_e32 v150, 16, v144
	v_and_b32_e32 v144, 0xffff0000, v144
	v_pk_mul_f32 v[86:87], v[86:87], v[148:149]
	s_waitcnt vmcnt(17)
	v_lshlrev_b32_e32 v148, 16, v140
	v_and_b32_e32 v149, 0xffff0000, v140
	v_lshlrev_b32_e32 v140, 16, v145
	v_rcp_f32_e32 v151, v144
	v_rcp_f32_e32 v144, v140
	v_and_b32_e32 v140, 0xffff0000, v145
	v_rcp_f32_e32 v145, v140
	v_lshlrev_b32_e32 v140, 16, v141
	v_and_b32_e32 v141, 0xffff0000, v141
	v_rcp_f32_e32 v150, v150
	v_pk_mul_f32 v[140:141], v[144:145], v[140:141]
	v_lshlrev_b32_e32 v144, 16, v146
	v_and_b32_e32 v145, 0xffff0000, v146
	v_rcp_f32_e32 v144, v144
	v_rcp_f32_e32 v145, v145
	v_pk_mul_f32 v[82:83], v[82:83], v[140:141]
	v_lshlrev_b32_e32 v140, 16, v142
	v_and_b32_e32 v141, 0xffff0000, v142
	v_lshlrev_b32_e32 v142, 16, v147
	v_pk_mul_f32 v[140:141], v[144:145], v[140:141]
	v_rcp_f32_e32 v144, v142
	v_and_b32_e32 v142, 0xffff0000, v147
	v_rcp_f32_e32 v145, v142
	v_pk_mul_f32 v[76:77], v[76:77], v[140:141]
	v_lshlrev_b32_e32 v140, 16, v143
	v_and_b32_e32 v141, 0xffff0000, v143
	v_pk_mul_f32 v[140:141], v[144:145], v[140:141]
	s_add_u32 s88, s90, 0xffefe000
	s_addc_u32 s89, s91, -1
	global_load_dwordx4 v[144:147], v251, s[88:89] nt
	s_waitcnt vmcnt(17)
	v_lshlrev_b32_e32 v142, 16, v136
	v_and_b32_e32 v136, 0xffff0000, v136
	v_pk_mul_f32 v[78:79], v[78:79], v[140:141]
	s_waitcnt vmcnt(16)
	v_lshlrev_b32_e32 v140, 16, v132
	v_and_b32_e32 v141, 0xffff0000, v132
	v_lshlrev_b32_e32 v132, 16, v137
	v_rcp_f32_e32 v143, v136
	v_rcp_f32_e32 v136, v132
	v_and_b32_e32 v132, 0xffff0000, v137
	v_rcp_f32_e32 v137, v132
	v_lshlrev_b32_e32 v132, 16, v133
	v_and_b32_e32 v133, 0xffff0000, v133
	v_rcp_f32_e32 v142, v142
	v_pk_mul_f32 v[132:133], v[136:137], v[132:133]
	v_lshlrev_b32_e32 v136, 16, v138
	v_and_b32_e32 v137, 0xffff0000, v138
	v_rcp_f32_e32 v136, v136
	v_rcp_f32_e32 v137, v137
	v_pk_mul_f32 v[74:75], v[74:75], v[132:133]
	v_lshlrev_b32_e32 v132, 16, v134
	v_and_b32_e32 v133, 0xffff0000, v134
	v_lshlrev_b32_e32 v134, 16, v139
	v_pk_mul_f32 v[132:133], v[136:137], v[132:133]
	v_rcp_f32_e32 v136, v134
	v_and_b32_e32 v134, 0xffff0000, v139
	v_rcp_f32_e32 v137, v134
	v_pk_mul_f32 v[68:69], v[68:69], v[132:133]
	v_lshlrev_b32_e32 v132, 16, v135
	v_and_b32_e32 v133, 0xffff0000, v135
	v_pk_mul_f32 v[182:183], v[188:189], v[182:183]
	v_pk_mul_f32 v[172:173], v[174:175], v[172:173]
	v_pk_mul_f32 v[164:165], v[166:167], v[164:165]
	v_pk_mul_f32 v[156:157], v[158:159], v[156:157]
	v_pk_mul_f32 v[148:149], v[150:151], v[148:149]
	v_pk_mul_f32 v[140:141], v[142:143], v[140:141]
	v_pk_mul_f32 v[132:133], v[136:137], v[132:133]
	v_pk_mul_f32 v[112:113], v[112:113], v[182:183]
	v_pk_mul_f32 v[104:105], v[104:105], v[172:173]
	v_pk_mul_f32 v[96:97], v[96:97], v[164:165]
	v_pk_mul_f32 v[88:89], v[88:89], v[156:157]
	v_pk_mul_f32 v[80:81], v[80:81], v[148:149]
	v_pk_mul_f32 v[72:73], v[72:73], v[140:141]
	v_pk_mul_f32 v[70:71], v[70:71], v[132:133]
	s_mov_b32 s2, 0xffef2000
	s_mov_b32 s2, 0xffff2000
	s_mov_b32 s2, 0xffef4000
	s_waitcnt vmcnt(15)
	v_lshlrev_b32_e32 v182, 16, v222
	v_and_b32_e32 v222, 0xffff0000, v222
	v_rcp_f32_e32 v183, v222
	v_lshlrev_b32_e32 v222, 16, v223
	v_and_b32_e32 v223, 0xffff0000, v223
	v_rcp_f32_e32 v222, v222
	v_rcp_f32_e32 v223, v223
	s_waitcnt vmcnt(4)
	v_lshlrev_b32_e32 v188, 16, v176
	v_and_b32_e32 v189, 0xffff0000, v176
	v_lshlrev_b32_e32 v176, 16, v177
	v_and_b32_e32 v177, 0xffff0000, v177
	v_pk_mul_f32 v[222:223], v[222:223], v[176:177]
	v_lshlrev_b32_e32 v176, 16, v224
	v_and_b32_e32 v224, 0xffff0000, v224
	v_rcp_f32_e32 v176, v176
	v_rcp_f32_e32 v177, v224
	v_lshlrev_b32_e32 v224, 16, v225
	v_and_b32_e32 v225, 0xffff0000, v225
	v_rcp_f32_e32 v224, v224
	v_rcp_f32_e32 v225, v225
	v_pk_mul_f32 v[66:67], v[66:67], v[222:223]
	v_lshlrev_b32_e32 v222, 16, v178
	v_and_b32_e32 v223, 0xffff0000, v178
	v_pk_mul_f32 v[222:223], v[176:177], v[222:223]
	v_rcp_f32_e32 v182, v182
	v_pk_mul_f32 v[60:61], v[60:61], v[222:223]
	v_lshlrev_b32_e32 v222, 16, v179
	v_and_b32_e32 v223, 0xffff0000, v179
	v_pk_mul_f32 v[222:223], v[224:225], v[222:223]
	s_waitcnt vmcnt(8)
	v_lshlrev_b32_e32 v224, 16, v196
	v_and_b32_e32 v225, 0xffff0000, v196
	v_rcp_f32_e32 v224, v224
	v_rcp_f32_e32 v225, v225
	v_pk_mul_f32 v[62:63], v[62:63], v[222:223]
	s_waitcnt vmcnt(7)
	v_lshlrev_b32_e32 v222, 16, v202
	v_and_b32_e32 v223, 0xffff0000, v202
	v_pk_mul_f32 v[222:223], v[224:225], v[222:223]
	v_lshlrev_b32_e32 v224, 16, v197
	v_and_b32_e32 v225, 0xffff0000, v197
	v_rcp_f32_e32 v224, v224
	v_rcp_f32_e32 v225, v225
	v_pk_mul_f32 v[56:57], v[56:57], v[222:223]
	v_lshlrev_b32_e32 v222, 16, v203
	v_and_b32_e32 v223, 0xffff0000, v203
	v_pk_mul_f32 v[222:223], v[224:225], v[222:223]
	v_lshlrev_b32_e32 v224, 16, v198
	v_and_b32_e32 v225, 0xffff0000, v198
	v_rcp_f32_e32 v224, v224
	v_rcp_f32_e32 v225, v225
	v_pk_mul_f32 v[58:59], v[58:59], v[222:223]
	v_lshlrev_b32_e32 v222, 16, v204
	v_and_b32_e32 v223, 0xffff0000, v204
	v_pk_mul_f32 v[222:223], v[224:225], v[222:223]
	v_lshlrev_b32_e32 v224, 16, v199
	v_and_b32_e32 v225, 0xffff0000, v199
	v_rcp_f32_e32 v224, v224
	v_rcp_f32_e32 v225, v225
	v_pk_mul_f32 v[52:53], v[52:53], v[222:223]
	v_lshlrev_b32_e32 v222, 16, v205
	v_and_b32_e32 v223, 0xffff0000, v205
	v_pk_mul_f32 v[222:223], v[224:225], v[222:223]
	s_waitcnt vmcnt(6)
	v_lshlrev_b32_e32 v224, 16, v206
	v_and_b32_e32 v225, 0xffff0000, v206
	v_rcp_f32_e32 v224, v224
	v_rcp_f32_e32 v225, v225
	v_pk_mul_f32 v[54:55], v[54:55], v[222:223]
	s_waitcnt vmcnt(5)
	v_lshlrev_b32_e32 v222, 16, v210
	v_and_b32_e32 v223, 0xffff0000, v210
	v_pk_mul_f32 v[222:223], v[224:225], v[222:223]
	v_lshlrev_b32_e32 v224, 16, v207
	v_and_b32_e32 v225, 0xffff0000, v207
	v_rcp_f32_e32 v224, v224
	v_rcp_f32_e32 v225, v225
	v_pk_mul_f32 v[48:49], v[48:49], v[222:223]
	v_lshlrev_b32_e32 v222, 16, v211
	v_and_b32_e32 v223, 0xffff0000, v211
	v_pk_mul_f32 v[222:223], v[224:225], v[222:223]
	v_lshlrev_b32_e32 v224, 16, v208
	v_and_b32_e32 v225, 0xffff0000, v208
	v_rcp_f32_e32 v224, v224
	v_rcp_f32_e32 v225, v225
	v_pk_mul_f32 v[50:51], v[50:51], v[222:223]
	v_lshlrev_b32_e32 v222, 16, v212
	v_and_b32_e32 v223, 0xffff0000, v212
	v_pk_mul_f32 v[222:223], v[224:225], v[222:223]
	v_lshlrev_b32_e32 v224, 16, v209
	v_and_b32_e32 v225, 0xffff0000, v209
	v_rcp_f32_e32 v224, v224
	v_rcp_f32_e32 v225, v225
	v_pk_mul_f32 v[44:45], v[44:45], v[222:223]
	v_lshlrev_b32_e32 v222, 16, v213
	v_and_b32_e32 v223, 0xffff0000, v213
	v_pk_mul_f32 v[222:223], v[224:225], v[222:223]
	s_waitcnt vmcnt(3)
	v_lshlrev_b32_e32 v224, 16, v168
	v_and_b32_e32 v168, 0xffff0000, v168
	v_pk_mul_f32 v[46:47], v[46:47], v[222:223]
	s_waitcnt vmcnt(14)
	v_lshlrev_b32_e32 v222, 16, v226
	v_and_b32_e32 v223, 0xffff0000, v226
	v_lshlrev_b32_e32 v226, 16, v169
	v_rcp_f32_e32 v225, v168
	v_rcp_f32_e32 v168, v226
	v_and_b32_e32 v226, 0xffff0000, v169
	v_rcp_f32_e32 v169, v226
	v_lshlrev_b32_e32 v226, 16, v227
	v_and_b32_e32 v227, 0xffff0000, v227
	v_rcp_f32_e32 v224, v224
	v_pk_mul_f32 v[226:227], v[168:169], v[226:227]
	v_lshlrev_b32_e32 v168, 16, v170
	v_and_b32_e32 v169, 0xffff0000, v170
	v_rcp_f32_e32 v168, v168
	v_rcp_f32_e32 v169, v169
	v_pk_mul_f32 v[42:43], v[42:43], v[226:227]
	v_lshlrev_b32_e32 v226, 16, v228
	v_and_b32_e32 v227, 0xffff0000, v228
	v_lshlrev_b32_e32 v228, 16, v171
	v_pk_mul_f32 v[226:227], v[168:169], v[226:227]
	v_rcp_f32_e32 v168, v228
	v_and_b32_e32 v228, 0xffff0000, v171
	v_rcp_f32_e32 v169, v228
	v_pk_mul_f32 v[36:37], v[36:37], v[226:227]
	v_lshlrev_b32_e32 v226, 16, v229
	v_and_b32_e32 v227, 0xffff0000, v229
	v_pk_mul_f32 v[226:227], v[168:169], v[226:227]
	s_waitcnt vmcnt(2)
	v_lshlrev_b32_e32 v228, 16, v160
	v_and_b32_e32 v160, 0xffff0000, v160
	v_pk_mul_f32 v[38:39], v[38:39], v[226:227]
	s_waitcnt vmcnt(13)
	v_lshlrev_b32_e32 v226, 16, v230
	v_and_b32_e32 v227, 0xffff0000, v230
	v_lshlrev_b32_e32 v230, 16, v161
	v_rcp_f32_e32 v229, v160
	v_rcp_f32_e32 v160, v230
	v_and_b32_e32 v230, 0xffff0000, v161
	v_rcp_f32_e32 v161, v230
	v_lshlrev_b32_e32 v230, 16, v231
	v_and_b32_e32 v231, 0xffff0000, v231
	v_rcp_f32_e32 v228, v228
	v_pk_mul_f32 v[230:231], v[160:161], v[230:231]
	v_lshlrev_b32_e32 v160, 16, v162
	v_and_b32_e32 v161, 0xffff0000, v162
	v_rcp_f32_e32 v160, v160
	v_rcp_f32_e32 v161, v161
	v_pk_mul_f32 v[34:35], v[34:35], v[230:231]
	v_lshlrev_b32_e32 v230, 16, v232
	v_and_b32_e32 v231, 0xffff0000, v232
	v_lshlrev_b32_e32 v232, 16, v163
	v_pk_mul_f32 v[230:231], v[160:161], v[230:231]
	v_rcp_f32_e32 v160, v232
	v_and_b32_e32 v232, 0xffff0000, v163
	v_rcp_f32_e32 v161, v232
	v_pk_mul_f32 v[28:29], v[28:29], v[230:231]
	v_lshlrev_b32_e32 v230, 16, v233
	v_and_b32_e32 v231, 0xffff0000, v233
	v_pk_mul_f32 v[230:231], v[160:161], v[230:231]
	s_waitcnt vmcnt(1)
	v_lshlrev_b32_e32 v232, 16, v152
	v_and_b32_e32 v152, 0xffff0000, v152
	v_pk_mul_f32 v[30:31], v[30:31], v[230:231]
	s_waitcnt vmcnt(12)
	v_lshlrev_b32_e32 v230, 16, v234
	v_and_b32_e32 v231, 0xffff0000, v234
	v_lshlrev_b32_e32 v234, 16, v153
	v_rcp_f32_e32 v233, v152
	v_rcp_f32_e32 v152, v234
	v_and_b32_e32 v234, 0xffff0000, v153
	v_rcp_f32_e32 v153, v234
	v_lshlrev_b32_e32 v234, 16, v235
	v_and_b32_e32 v235, 0xffff0000, v235
	v_rcp_f32_e32 v232, v232
	v_pk_mul_f32 v[234:235], v[152:153], v[234:235]
	v_lshlrev_b32_e32 v152, 16, v154
	v_and_b32_e32 v153, 0xffff0000, v154
	v_rcp_f32_e32 v152, v152
	v_rcp_f32_e32 v153, v153
	v_pk_mul_f32 v[26:27], v[26:27], v[234:235]
	v_lshlrev_b32_e32 v234, 16, v236
	v_and_b32_e32 v235, 0xffff0000, v236
	v_lshlrev_b32_e32 v236, 16, v155
	v_pk_mul_f32 v[234:235], v[152:153], v[234:235]
	v_rcp_f32_e32 v152, v236
	v_and_b32_e32 v236, 0xffff0000, v155
	v_rcp_f32_e32 v153, v236
	v_pk_mul_f32 v[20:21], v[20:21], v[234:235]
	v_lshlrev_b32_e32 v234, 16, v237
	v_and_b32_e32 v235, 0xffff0000, v237
	v_pk_mul_f32 v[234:235], v[152:153], v[234:235]
	s_waitcnt vmcnt(0)
	v_lshlrev_b32_e32 v236, 16, v144
	v_and_b32_e32 v144, 0xffff0000, v144
	v_pk_mul_f32 v[22:23], v[22:23], v[234:235]
	s_waitcnt vmcnt(11)
	v_lshlrev_b32_e32 v234, 16, v238
	v_and_b32_e32 v235, 0xffff0000, v238
	v_lshlrev_b32_e32 v238, 16, v145
	v_rcp_f32_e32 v237, v144
	v_rcp_f32_e32 v144, v238
	v_and_b32_e32 v238, 0xffff0000, v145
	v_rcp_f32_e32 v145, v238
	v_lshlrev_b32_e32 v238, 16, v239
	v_and_b32_e32 v239, 0xffff0000, v239
	v_rcp_f32_e32 v236, v236
	v_pk_mul_f32 v[238:239], v[144:145], v[238:239]
	v_lshlrev_b32_e32 v144, 16, v146
	v_and_b32_e32 v145, 0xffff0000, v146
	v_rcp_f32_e32 v144, v144
	v_rcp_f32_e32 v145, v145
	v_pk_mul_f32 v[18:19], v[18:19], v[238:239]
	v_lshlrev_b32_e32 v238, 16, v240
	v_and_b32_e32 v239, 0xffff0000, v240
	v_lshlrev_b32_e32 v240, 16, v147
	v_pk_mul_f32 v[238:239], v[144:145], v[238:239]
	v_rcp_f32_e32 v144, v240
	v_and_b32_e32 v240, 0xffff0000, v147
	v_rcp_f32_e32 v145, v240
	v_pk_mul_f32 v[12:13], v[12:13], v[238:239]
	v_lshlrev_b32_e32 v238, 16, v241
	v_and_b32_e32 v239, 0xffff0000, v241
	v_pk_mul_f32 v[238:239], v[144:145], v[238:239]
	s_waitcnt vmcnt(10)
	v_lshlrev_b32_e32 v240, 16, v242
	v_and_b32_e32 v242, 0xffff0000, v242
	v_pk_mul_f32 v[14:15], v[14:15], v[238:239]
	s_waitcnt vmcnt(9)
	v_lshlrev_b32_e32 v238, 16, v246
	v_and_b32_e32 v239, 0xffff0000, v246
	v_lshlrev_b32_e32 v246, 16, v243
	v_rcp_f32_e32 v241, v242
	v_rcp_f32_e32 v242, v246
	v_and_b32_e32 v246, 0xffff0000, v243
	v_rcp_f32_e32 v243, v246
	v_lshlrev_b32_e32 v246, 16, v247
	v_and_b32_e32 v247, 0xffff0000, v247
	v_rcp_f32_e32 v240, v240
	v_pk_mul_f32 v[246:247], v[242:243], v[246:247]
	v_lshlrev_b32_e32 v242, 16, v244
	v_and_b32_e32 v243, 0xffff0000, v244
	v_rcp_f32_e32 v242, v242
	v_rcp_f32_e32 v243, v243
	v_pk_mul_f32 v[10:11], v[10:11], v[246:247]
	v_lshlrev_b32_e32 v246, 16, v248
	v_and_b32_e32 v247, 0xffff0000, v248
	v_lshlrev_b32_e32 v248, 16, v245
	v_pk_mul_f32 v[246:247], v[242:243], v[246:247]
	v_rcp_f32_e32 v242, v248
	v_and_b32_e32 v248, 0xffff0000, v245
	v_rcp_f32_e32 v243, v248
	v_pk_mul_f32 v[4:5], v[4:5], v[246:247]
	v_lshlrev_b32_e32 v246, 16, v249
	v_and_b32_e32 v247, 0xffff0000, v249
	v_pk_mul_f32 v[182:183], v[182:183], v[188:189]
	v_pk_mul_f32 v[222:223], v[224:225], v[222:223]
	v_pk_mul_f32 v[226:227], v[228:229], v[226:227]
	v_pk_mul_f32 v[230:231], v[232:233], v[230:231]
	v_pk_mul_f32 v[234:235], v[236:237], v[234:235]
	v_pk_mul_f32 v[238:239], v[240:241], v[238:239]
	v_pk_mul_f32 v[246:247], v[242:243], v[246:247]
	v_pk_mul_f32 v[64:65], v[64:65], v[182:183]
	v_pk_mul_f32 v[40:41], v[40:41], v[222:223]
	v_pk_mul_f32 v[32:33], v[32:33], v[226:227]
	v_pk_mul_f32 v[24:25], v[24:25], v[230:231]
	v_pk_mul_f32 v[16:17], v[16:17], v[234:235]
	v_pk_mul_f32 v[8:9], v[8:9], v[238:239]
	v_pk_mul_f32 v[6:7], v[6:7], v[246:247]
